# P3 K-loop touches the residual x tile in reverse consumption order (rows read first are touched last); on top of bias-in-LDS
# baseline (speedup 1.0000x reference)
.LBB0_495:
	v_add_u32_e32 v147, s53, v145
	ds_read_b128 v[148:151], v147
	ds_read_b128 v[152:155], v147 offset:1024
	ds_read_b128 v[156:159], v147 offset:2048
	ds_read_b128 v[160:163], v147 offset:3072
	v_add_u32_e32 v147, s54, v145
	s_add_u32 s34, s16, s30
	ds_read_b128 v[164:167], v147
	ds_read_b128 v[172:175], v147 offset:1024
	ds_read_b128 v[176:179], v147 offset:2048
	ds_read_b128 v[180:183], v147 offset:3072
	s_addc_u32 s35, s17, s31
	s_add_u32 s34, s34, 0x100
	s_addc_u32 s35, s35, 0
	s_add_u32 s59, s27, s30
	s_addc_u32 s60, s55, s31
	s_cmpk_eq_i32 s30, 0xf00
	s_cselect_b32 s37, s21, s35
	s_cselect_b32 s36, s23, s34
	s_cselect_b32 s35, s56, s60
	s_cselect_b32 s34, s57, s59
	v_lshl_add_u64 v[168:169], v[140:141], 0, s[30:31]
	s_add_i32 m0, s40, 0xc000
	ds_read_b128 v[184:187], v146
	ds_read_b128 v[188:191], v146 offset:1024
	ds_read_b128 v[192:195], v146 offset:2048
	ds_read_b128 v[196:199], v146 offset:3072
	ds_read_b128 v[202:205], v146 offset:4096
	ds_read_b128 v[206:209], v146 offset:5120
	ds_read_b128 v[210:213], v146 offset:6144
	ds_read_b128 v[214:217], v146 offset:7168
	global_load_lds_dwordx4 v[168:169], off
	v_lshl_add_u64 v[168:169], v[142:143], 0, s[30:31]
	s_add_i32 m0, s40, 0xe000
	s_nop 0
	global_load_lds_dwordx4 v[168:169], off
	s_waitcnt vmcnt(8)
	s_sub_i32 s62, 28, s58
	s_lshr_b32 s62, s62, 1
	s_and_b32 s63, s62, 1
	s_lshl_b32 s63, s63, 6
	s_bfe_u32 s73, s62, 0x20001
	s_lshl_b32 s73, s73, 4
	s_or_b32 s63, s63, s73
	s_lshr_b32 s62, s62, 3
	s_lshl_b32 s62, s62, 7
	s_or_b32 s62, s62, s63
	s_lshl_b32 s62, s62, 12
	v_add_u32_e32 v227, s62, v226
	global_load_dword v227, v227, s[44:45]
	s_waitcnt lgkmcnt(0)
	s_barrier
	s_setprio 1
	s_waitcnt lgkmcnt(0)
	v_mfma_f32_16x16x32_bf16 v[124:127], v[148:151], v[184:187], v[124:127]
	v_mfma_f32_16x16x32_bf16 v[120:123], v[156:159], v[184:187], v[120:123]
	v_mfma_f32_16x16x32_bf16 v[108:111], v[148:151], v[192:195], v[108:111]
	v_mfma_f32_16x16x32_bf16 v[104:107], v[156:159], v[192:195], v[104:107]
	v_mfma_f32_16x16x32_bf16 v[92:95], v[148:151], v[202:205], v[92:95]
	v_mfma_f32_16x16x32_bf16 v[88:91], v[156:159], v[202:205], v[88:91]
	v_mfma_f32_16x16x32_bf16 v[76:79], v[148:151], v[210:213], v[76:79]
	v_mfma_f32_16x16x32_bf16 v[72:75], v[156:159], v[210:213], v[72:75]
	v_mfma_f32_16x16x32_bf16 v[124:127], v[152:155], v[188:191], v[124:127]
	v_mfma_f32_16x16x32_bf16 v[120:123], v[160:163], v[188:191], v[120:123]
	v_mfma_f32_16x16x32_bf16 v[108:111], v[152:155], v[196:199], v[108:111]
	v_mfma_f32_16x16x32_bf16 v[104:107], v[160:163], v[196:199], v[104:107]
	v_mfma_f32_16x16x32_bf16 v[92:95], v[152:155], v[206:209], v[92:95]
	v_mfma_f32_16x16x32_bf16 v[88:91], v[160:163], v[206:209], v[88:91]
	v_mfma_f32_16x16x32_bf16 v[76:79], v[152:155], v[214:217], v[76:79]
	v_mfma_f32_16x16x32_bf16 v[72:75], v[160:163], v[214:217], v[72:75]
	s_setprio 0
	s_setprio 1
	v_mfma_f32_16x16x32_bf16 v[116:119], v[164:167], v[184:187], v[116:119]
	v_mfma_f32_16x16x32_bf16 v[112:115], v[176:179], v[184:187], v[112:115]
	v_mfma_f32_16x16x32_bf16 v[100:103], v[164:167], v[192:195], v[100:103]
	v_mfma_f32_16x16x32_bf16 v[96:99], v[176:179], v[192:195], v[96:99]
	v_mfma_f32_16x16x32_bf16 v[84:87], v[164:167], v[202:205], v[84:87]
	v_mfma_f32_16x16x32_bf16 v[80:83], v[176:179], v[202:205], v[80:83]
	v_mfma_f32_16x16x32_bf16 v[68:71], v[164:167], v[210:213], v[68:71]
	v_mfma_f32_16x16x32_bf16 v[64:67], v[176:179], v[210:213], v[64:67]
	v_mfma_f32_16x16x32_bf16 v[116:119], v[172:175], v[188:191], v[116:119]
	v_mfma_f32_16x16x32_bf16 v[112:115], v[180:183], v[188:191], v[112:115]
	v_mfma_f32_16x16x32_bf16 v[100:103], v[172:175], v[196:199], v[100:103]
	v_mfma_f32_16x16x32_bf16 v[96:99], v[180:183], v[196:199], v[96:99]
	v_mfma_f32_16x16x32_bf16 v[84:87], v[172:175], v[206:209], v[84:87]
	v_mfma_f32_16x16x32_bf16 v[80:83], v[180:183], v[206:209], v[80:83]
	v_mfma_f32_16x16x32_bf16 v[68:71], v[172:175], v[214:217], v[68:71]
	v_mfma_f32_16x16x32_bf16 v[64:67], v[180:183], v[214:217], v[64:67]
	s_setprio 0
	s_barrier
	s_add_i32 s59, s53, s39
	v_lshl_add_u64 v[168:169], s[34:35], 0, v[128:129]
	s_mov_b32 m0, s59
	ds_read_b128 v[184:187], v146 offset:16384
	ds_read_b128 v[188:191], v146 offset:17408
	ds_read_b128 v[192:195], v146 offset:18432
	ds_read_b128 v[196:199], v146 offset:19456
	ds_read_b128 v[202:205], v146 offset:20480
	ds_read_b128 v[206:209], v146 offset:21504
	ds_read_b128 v[210:213], v146 offset:22528
	ds_read_b128 v[214:217], v146 offset:23552
	global_load_lds_dwordx4 v[168:169], off
	s_add_i32 m0, s59, 0x2000
	s_add_u32 s60, s34, 0x80000
	v_lshl_add_u64 v[218:219], s[34:35], 0, v[130:131]
	s_addc_u32 s61, s35, 0
	s_add_i32 s59, s54, s39
	global_load_lds_dwordx4 v[218:219], off
	v_lshl_add_u64 v[220:221], s[60:61], 0, v[128:129]
	s_mov_b32 m0, s59
	v_lshl_add_u64 v[222:223], s[36:37], 0, v[130:131]
	global_load_lds_dwordx4 v[220:221], off
	v_lshl_add_u64 v[220:221], s[60:61], 0, v[130:131]
	s_add_i32 m0, s59, 0x2000
	s_nop 0
	global_load_lds_dwordx4 v[220:221], off
	v_lshl_add_u64 v[220:221], s[36:37], 0, v[128:129]
	s_mov_b32 m0, s40
	s_nop 0
	global_load_lds_dwordx4 v[220:221], off
	s_mov_b32 m0, s41
	s_nop 0
	global_load_lds_dwordx4 v[222:223], off
	s_waitcnt vmcnt(9)
	s_waitcnt lgkmcnt(0)
	s_barrier
	s_setprio 1
	s_waitcnt lgkmcnt(0)
	v_mfma_f32_16x16x32_bf16 v[60:63], v[148:151], v[184:187], v[60:63]
	v_mfma_f32_16x16x32_bf16 v[56:59], v[156:159], v[184:187], v[56:59]
	v_mfma_f32_16x16x32_bf16 v[44:47], v[148:151], v[192:195], v[44:47]
	v_mfma_f32_16x16x32_bf16 v[40:43], v[156:159], v[192:195], v[40:43]
	v_mfma_f32_16x16x32_bf16 v[28:31], v[148:151], v[202:205], v[28:31]
	v_mfma_f32_16x16x32_bf16 v[24:27], v[156:159], v[202:205], v[24:27]
	v_mfma_f32_16x16x32_bf16 v[12:15], v[148:151], v[210:213], v[12:15]
	v_mfma_f32_16x16x32_bf16 v[8:11], v[156:159], v[210:213], v[8:11]
	v_mfma_f32_16x16x32_bf16 v[60:63], v[152:155], v[188:191], v[60:63]
	v_mfma_f32_16x16x32_bf16 v[56:59], v[160:163], v[188:191], v[56:59]
	v_mfma_f32_16x16x32_bf16 v[44:47], v[152:155], v[196:199], v[44:47]
	v_mfma_f32_16x16x32_bf16 v[40:43], v[160:163], v[196:199], v[40:43]
	v_mfma_f32_16x16x32_bf16 v[28:31], v[152:155], v[206:209], v[28:31]
	v_mfma_f32_16x16x32_bf16 v[24:27], v[160:163], v[206:209], v[24:27]
	v_mfma_f32_16x16x32_bf16 v[12:15], v[152:155], v[214:217], v[12:15]
	v_mfma_f32_16x16x32_bf16 v[8:11], v[160:163], v[214:217], v[8:11]
	s_setprio 0
	s_setprio 1
	v_mfma_f32_16x16x32_bf16 v[52:55], v[164:167], v[184:187], v[52:55]
	v_mfma_f32_16x16x32_bf16 v[48:51], v[176:179], v[184:187], v[48:51]
	v_mfma_f32_16x16x32_bf16 v[36:39], v[164:167], v[192:195], v[36:39]
	v_mfma_f32_16x16x32_bf16 v[32:35], v[176:179], v[192:195], v[32:35]
	v_mfma_f32_16x16x32_bf16 v[20:23], v[164:167], v[202:205], v[20:23]
	v_mfma_f32_16x16x32_bf16 v[16:19], v[176:179], v[202:205], v[16:19]
	v_mfma_f32_16x16x32_bf16 v[4:7], v[164:167], v[210:213], v[4:7]
	v_mfma_f32_16x16x32_bf16 v[0:3], v[176:179], v[210:213], v[0:3]
	v_mfma_f32_16x16x32_bf16 v[52:55], v[172:175], v[188:191], v[52:55]
	v_mfma_f32_16x16x32_bf16 v[48:51], v[180:183], v[188:191], v[48:51]
	v_mfma_f32_16x16x32_bf16 v[36:39], v[172:175], v[196:199], v[36:39]
	v_mfma_f32_16x16x32_bf16 v[32:35], v[180:183], v[196:199], v[32:35]
	v_mfma_f32_16x16x32_bf16 v[20:23], v[172:175], v[206:209], v[20:23]
	v_mfma_f32_16x16x32_bf16 v[16:19], v[180:183], v[206:209], v[16:19]
	v_mfma_f32_16x16x32_bf16 v[4:7], v[172:175], v[214:217], v[4:7]
	v_mfma_f32_16x16x32_bf16 v[0:3], v[180:183], v[214:217], v[0:3]
	s_setprio 0
	s_barrier
	s_add_i32 s59, 0, 0x18000
	v_add_u32_e32 v147, s59, v145
	s_add_i32 s60, 0, 0x1c000
	ds_read_b128 v[148:151], v147
	ds_read_b128 v[152:155], v147 offset:1024
	ds_read_b128 v[156:159], v147 offset:2048
	ds_read_b128 v[160:163], v147 offset:3072
	v_add_u32_e32 v147, s60, v145
	ds_read_b128 v[164:167], v147
	ds_read_b128 v[172:175], v147 offset:1024
	ds_read_b128 v[176:179], v147 offset:2048
	ds_read_b128 v[180:183], v147 offset:3072
	s_add_u32 s36, s36, 0x80000
	s_addc_u32 s37, s37, 0
	s_mov_b32 m0, s43
	v_lshl_add_u64 v[224:225], s[36:37], 0, v[128:129]
	ds_read_b128 v[184:187], v146 offset:32768
	ds_read_b128 v[188:191], v146 offset:33792
	ds_read_b128 v[192:195], v146 offset:34816
	ds_read_b128 v[196:199], v146 offset:35840
	ds_read_b128 v[202:205], v146 offset:36864
	ds_read_b128 v[206:209], v146 offset:37888
	ds_read_b128 v[210:213], v146 offset:38912
	ds_read_b128 v[214:217], v146 offset:39936
	global_load_lds_dwordx4 v[224:225], off
	v_lshl_add_u64 v[224:225], s[36:37], 0, v[130:131]
	s_mov_b32 m0, s48
	s_nop 0
	global_load_lds_dwordx4 v[224:225], off
	s_waitcnt vmcnt(9)
	s_waitcnt lgkmcnt(0)
	s_barrier
	s_setprio 1
	s_waitcnt lgkmcnt(0)
	v_mfma_f32_16x16x32_bf16 v[124:127], v[148:151], v[184:187], v[124:127]
	v_mfma_f32_16x16x32_bf16 v[120:123], v[156:159], v[184:187], v[120:123]
	v_mfma_f32_16x16x32_bf16 v[108:111], v[148:151], v[192:195], v[108:111]
	v_mfma_f32_16x16x32_bf16 v[104:107], v[156:159], v[192:195], v[104:107]
	v_mfma_f32_16x16x32_bf16 v[92:95], v[148:151], v[202:205], v[92:95]
	v_mfma_f32_16x16x32_bf16 v[88:91], v[156:159], v[202:205], v[88:91]
	v_mfma_f32_16x16x32_bf16 v[76:79], v[148:151], v[210:213], v[76:79]
	v_mfma_f32_16x16x32_bf16 v[72:75], v[156:159], v[210:213], v[72:75]
	v_mfma_f32_16x16x32_bf16 v[124:127], v[152:155], v[188:191], v[124:127]
	v_mfma_f32_16x16x32_bf16 v[120:123], v[160:163], v[188:191], v[120:123]
	v_mfma_f32_16x16x32_bf16 v[108:111], v[152:155], v[196:199], v[108:111]
	v_mfma_f32_16x16x32_bf16 v[104:107], v[160:163], v[196:199], v[104:107]
	v_mfma_f32_16x16x32_bf16 v[92:95], v[152:155], v[206:209], v[92:95]
	v_mfma_f32_16x16x32_bf16 v[88:91], v[160:163], v[206:209], v[88:91]
	v_mfma_f32_16x16x32_bf16 v[76:79], v[152:155], v[214:217], v[76:79]
	v_mfma_f32_16x16x32_bf16 v[72:75], v[160:163], v[214:217], v[72:75]
	s_setprio 0
	s_setprio 1
	v_mfma_f32_16x16x32_bf16 v[116:119], v[164:167], v[184:187], v[116:119]
	v_mfma_f32_16x16x32_bf16 v[112:115], v[176:179], v[184:187], v[112:115]
	v_mfma_f32_16x16x32_bf16 v[100:103], v[164:167], v[192:195], v[100:103]
	v_mfma_f32_16x16x32_bf16 v[96:99], v[176:179], v[192:195], v[96:99]
	v_mfma_f32_16x16x32_bf16 v[84:87], v[164:167], v[202:205], v[84:87]
	v_mfma_f32_16x16x32_bf16 v[80:83], v[176:179], v[202:205], v[80:83]
	v_mfma_f32_16x16x32_bf16 v[68:71], v[164:167], v[210:213], v[68:71]
	v_mfma_f32_16x16x32_bf16 v[64:67], v[176:179], v[210:213], v[64:67]
	v_mfma_f32_16x16x32_bf16 v[116:119], v[172:175], v[188:191], v[116:119]
	v_mfma_f32_16x16x32_bf16 v[112:115], v[180:183], v[188:191], v[112:115]
	v_mfma_f32_16x16x32_bf16 v[100:103], v[172:175], v[196:199], v[100:103]
	v_mfma_f32_16x16x32_bf16 v[96:99], v[180:183], v[196:199], v[96:99]
	v_mfma_f32_16x16x32_bf16 v[84:87], v[172:175], v[206:209], v[84:87]
	v_mfma_f32_16x16x32_bf16 v[80:83], v[180:183], v[206:209], v[80:83]
	v_mfma_f32_16x16x32_bf16 v[68:71], v[172:175], v[214:217], v[68:71]
	v_mfma_f32_16x16x32_bf16 v[64:67], v[180:183], v[214:217], v[64:67]
	s_setprio 0
	s_barrier
	s_add_i32 s36, s59, s39
	v_lshl_add_u64 v[168:169], v[168:169], 0, s[18:19]
	s_mov_b32 m0, s36
	ds_read_b128 v[184:187], v146 offset:49152
	ds_read_b128 v[188:191], v146 offset:50176
	ds_read_b128 v[192:195], v146 offset:51200
	ds_read_b128 v[196:199], v146 offset:52224
	ds_read_b128 v[202:205], v146 offset:53248
	ds_read_b128 v[206:209], v146 offset:54272
	ds_read_b128 v[210:213], v146 offset:55296
	ds_read_b128 v[214:217], v146 offset:56320
	global_load_lds_dwordx4 v[168:169], off
	s_add_i32 m0, s36, 0x2000
	s_add_u32 s34, s34, 0x80080
	v_lshl_add_u64 v[168:169], v[218:219], 0, s[18:19]
	s_addc_u32 s35, s35, 0
	s_add_i32 s36, s60, s39
	global_load_lds_dwordx4 v[168:169], off
	v_lshl_add_u64 v[168:169], s[34:35], 0, v[128:129]
	s_mov_b32 m0, s36
	s_nop 0
	global_load_lds_dwordx4 v[168:169], off
	v_lshl_add_u64 v[168:169], s[34:35], 0, v[130:131]
	s_add_i32 m0, s36, 0x2000
	s_nop 0
	global_load_lds_dwordx4 v[168:169], off
	v_lshl_add_u64 v[168:169], v[220:221], 0, s[18:19]
	s_mov_b32 m0, s49
	s_nop 0
	global_load_lds_dwordx4 v[168:169], off
	v_lshl_add_u64 v[168:169], v[222:223], 0, s[18:19]
	s_mov_b32 m0, s50
	s_nop 0
	global_load_lds_dwordx4 v[168:169], off
	s_waitcnt vmcnt(8)
	s_waitcnt lgkmcnt(0)
	s_barrier
	s_setprio 1
	s_waitcnt lgkmcnt(0)
	v_mfma_f32_16x16x32_bf16 v[60:63], v[148:151], v[184:187], v[60:63]
	v_mfma_f32_16x16x32_bf16 v[56:59], v[156:159], v[184:187], v[56:59]
	v_mfma_f32_16x16x32_bf16 v[44:47], v[148:151], v[192:195], v[44:47]
	v_mfma_f32_16x16x32_bf16 v[40:43], v[156:159], v[192:195], v[40:43]
	v_mfma_f32_16x16x32_bf16 v[28:31], v[148:151], v[202:205], v[28:31]
	v_mfma_f32_16x16x32_bf16 v[24:27], v[156:159], v[202:205], v[24:27]
	v_mfma_f32_16x16x32_bf16 v[12:15], v[148:151], v[210:213], v[12:15]
	v_mfma_f32_16x16x32_bf16 v[8:11], v[156:159], v[210:213], v[8:11]
	v_mfma_f32_16x16x32_bf16 v[60:63], v[152:155], v[188:191], v[60:63]
	v_mfma_f32_16x16x32_bf16 v[56:59], v[160:163], v[188:191], v[56:59]
	v_mfma_f32_16x16x32_bf16 v[44:47], v[152:155], v[196:199], v[44:47]
	v_mfma_f32_16x16x32_bf16 v[40:43], v[160:163], v[196:199], v[40:43]
	v_mfma_f32_16x16x32_bf16 v[28:31], v[152:155], v[206:209], v[28:31]
	v_mfma_f32_16x16x32_bf16 v[24:27], v[160:163], v[206:209], v[24:27]
	v_mfma_f32_16x16x32_bf16 v[12:15], v[152:155], v[214:217], v[12:15]
	v_mfma_f32_16x16x32_bf16 v[8:11], v[160:163], v[214:217], v[8:11]
	s_setprio 0
	s_setprio 1
	v_mfma_f32_16x16x32_bf16 v[52:55], v[164:167], v[184:187], v[52:55]
	v_mfma_f32_16x16x32_bf16 v[48:51], v[176:179], v[184:187], v[48:51]
	v_mfma_f32_16x16x32_bf16 v[36:39], v[164:167], v[192:195], v[36:39]
	v_mfma_f32_16x16x32_bf16 v[32:35], v[176:179], v[192:195], v[32:35]
	v_mfma_f32_16x16x32_bf16 v[20:23], v[164:167], v[202:205], v[20:23]
	v_mfma_f32_16x16x32_bf16 v[16:19], v[176:179], v[202:205], v[16:19]
	v_mfma_f32_16x16x32_bf16 v[4:7], v[164:167], v[210:213], v[4:7]
	v_mfma_f32_16x16x32_bf16 v[0:3], v[176:179], v[210:213], v[0:3]
	v_mfma_f32_16x16x32_bf16 v[52:55], v[172:175], v[188:191], v[52:55]
	v_mfma_f32_16x16x32_bf16 v[48:51], v[180:183], v[188:191], v[48:51]
	v_mfma_f32_16x16x32_bf16 v[36:39], v[172:175], v[196:199], v[36:39]
	v_mfma_f32_16x16x32_bf16 v[32:35], v[180:183], v[196:199], v[32:35]
	v_mfma_f32_16x16x32_bf16 v[20:23], v[172:175], v[206:209], v[20:23]
	v_mfma_f32_16x16x32_bf16 v[16:19], v[180:183], v[206:209], v[16:19]
	v_mfma_f32_16x16x32_bf16 v[4:7], v[172:175], v[214:217], v[4:7]
	v_mfma_f32_16x16x32_bf16 v[0:3], v[180:183], v[214:217], v[0:3]
	s_setprio 0
	s_barrier
	s_add_i32 s58, s58, 2
	s_add_u32 s30, s30, 0x100
	s_addc_u32 s31, s31, 0
	s_cmp_gt_u32 s58, 29
	s_cbranch_scc0 .LBB0_495
	s_add_u32 s30, s27, 0xffffff00
	s_addc_u32 s31, s55, -1
	s_andn2_b64 vcc, exec, s[4:5]
	s_cbranch_vccnz .LBB0_498
	v_mov_b32_e32 v0, 0
	s_mov_b32 s51, s20
	s_mov_b32 s14, s22
	s_mov_b64 s[16:17], s[28:29]
	s_mov_b32 s52, s26
	v_mov_b32_e32 v1, v0
	v_mov_b32_e32 v2, v0
	v_mov_b32_e32 v3, v0
	v_mov_b32_e32 v4, v0
	v_mov_b32_e32 v5, v0
	v_mov_b32_e32 v6, v0
	v_mov_b32_e32 v7, v0
	v_mov_b32_e32 v16, v0
	v_mov_b32_e32 v17, v0
	v_mov_b32_e32 v18, v0
	v_mov_b32_e32 v19, v0
	v_mov_b32_e32 v20, v0
	v_mov_b32_e32 v21, v0
	v_mov_b32_e32 v22, v0
	v_mov_b32_e32 v23, v0
	v_mov_b32_e32 v32, v0
	v_mov_b32_e32 v33, v0
	v_mov_b32_e32 v34, v0
	v_mov_b32_e32 v35, v0
	v_mov_b32_e32 v36, v0
	v_mov_b32_e32 v37, v0
	v_mov_b32_e32 v38, v0
	v_mov_b32_e32 v39, v0
	v_mov_b32_e32 v48, v0
	v_mov_b32_e32 v49, v0
	v_mov_b32_e32 v50, v0
	v_mov_b32_e32 v51, v0
	v_mov_b32_e32 v52, v0
	v_mov_b32_e32 v53, v0
	v_mov_b32_e32 v54, v0
	v_mov_b32_e32 v55, v0
	v_mov_b32_e32 v8, v0
	v_mov_b32_e32 v9, v0
	v_mov_b32_e32 v10, v0
	v_mov_b32_e32 v11, v0
	v_mov_b32_e32 v12, v0
	v_mov_b32_e32 v13, v0
	v_mov_b32_e32 v14, v0
	v_mov_b32_e32 v15, v0
	v_mov_b32_e32 v24, v0
	v_mov_b32_e32 v25, v0
	v_mov_b32_e32 v26, v0
	v_mov_b32_e32 v27, v0
	v_mov_b32_e32 v28, v0
	v_mov_b32_e32 v29, v0
	v_mov_b32_e32 v30, v0
	v_mov_b32_e32 v31, v0
	v_mov_b32_e32 v40, v0
	v_mov_b32_e32 v41, v0
	v_mov_b32_e32 v42, v0
	v_mov_b32_e32 v43, v0
	v_mov_b32_e32 v44, v0
	v_mov_b32_e32 v45, v0
	v_mov_b32_e32 v46, v0
	v_mov_b32_e32 v47, v0
	v_mov_b32_e32 v56, v0
	v_mov_b32_e32 v57, v0
	v_mov_b32_e32 v58, v0
	v_mov_b32_e32 v59, v0
	v_mov_b32_e32 v60, v0
	v_mov_b32_e32 v61, v0
	v_mov_b32_e32 v62, v0
	v_mov_b32_e32 v63, v0
	v_mov_b32_e32 v64, v0
	v_mov_b32_e32 v65, v0
	v_mov_b32_e32 v66, v0
	v_mov_b32_e32 v67, v0
	v_mov_b32_e32 v68, v0
	v_mov_b32_e32 v69, v0
	v_mov_b32_e32 v70, v0
	v_mov_b32_e32 v71, v0
	v_mov_b32_e32 v80, v0
	v_mov_b32_e32 v81, v0
	v_mov_b32_e32 v82, v0
	v_mov_b32_e32 v83, v0
	v_mov_b32_e32 v84, v0
	v_mov_b32_e32 v85, v0
	v_mov_b32_e32 v86, v0
	v_mov_b32_e32 v87, v0
	v_mov_b32_e32 v96, v0
	v_mov_b32_e32 v97, v0
	v_mov_b32_e32 v98, v0
	v_mov_b32_e32 v99, v0
	v_mov_b32_e32 v100, v0
	v_mov_b32_e32 v101, v0
	v_mov_b32_e32 v102, v0
	v_mov_b32_e32 v103, v0
	v_mov_b32_e32 v112, v0
	v_mov_b32_e32 v113, v0
	v_mov_b32_e32 v114, v0
	v_mov_b32_e32 v115, v0
	v_mov_b32_e32 v116, v0
	v_mov_b32_e32 v117, v0
	v_mov_b32_e32 v118, v0
	v_mov_b32_e32 v119, v0
	v_mov_b32_e32 v72, v0
	v_mov_b32_e32 v73, v0
	v_mov_b32_e32 v74, v0
	v_mov_b32_e32 v75, v0
	v_mov_b32_e32 v76, v0
	v_mov_b32_e32 v77, v0
	v_mov_b32_e32 v78, v0
	v_mov_b32_e32 v79, v0
	v_mov_b32_e32 v88, v0
	v_mov_b32_e32 v89, v0
	v_mov_b32_e32 v90, v0
	v_mov_b32_e32 v91, v0
	v_mov_b32_e32 v92, v0
	v_mov_b32_e32 v93, v0
	v_mov_b32_e32 v94, v0
	v_mov_b32_e32 v95, v0
	v_mov_b32_e32 v104, v0
	v_mov_b32_e32 v105, v0
	v_mov_b32_e32 v106, v0
	v_mov_b32_e32 v107, v0
	v_mov_b32_e32 v108, v0
	v_mov_b32_e32 v109, v0
	v_mov_b32_e32 v110, v0
	v_mov_b32_e32 v111, v0
	v_mov_b32_e32 v120, v0
	v_mov_b32_e32 v121, v0
	v_mov_b32_e32 v122, v0
	v_mov_b32_e32 v123, v0
	v_mov_b32_e32 v124, v0
	v_mov_b32_e32 v125, v0
	v_mov_b32_e32 v126, v0
	v_mov_b32_e32 v127, v0
	s_andn2_b64 vcc, exec, s[0:1]
	s_cbranch_vccnz .LBB0_499
	s_branch .LBB0_500
